# v5 + scan unit prologue: per-unit parameter/weight staging loads issued in two batches (one wait each) instead of 8 dependent load-wait-ds_write round trips
# speedup vs baseline: 1.0048x; 1.0048x over previous
.LBB0_478:
	s_or_b64 exec, exec, s[0:1]
	s_waitcnt lgkmcnt(0)
	s_barrier
	s_waitcnt vmcnt(6)
	ds_read_b32 v0, v41 offset:4
	s_movk_i32 s0, 0xff
	s_waitcnt lgkmcnt(0)
	v_cmp_lt_i32_e32 vcc, s0, v0
	v_readfirstlane_b32 s59, v0
	s_mov_b64 s[0:1], -1
	s_cbranch_vccnz .LBB0_473
	s_setprio 3
	s_lshl_b32 s0, s59, 6
	s_and_b32 s58, s0, 0x3c0
	s_barrier
	s_and_saveexec_b64 s[0:1], s[20:21]
	s_cbranch_execz .LBB0_481
	s_lshl_b32 s28, s58, 2
	v_lshl_add_u64 v[0:1], v[44:45], 0, s[28:29]
	global_load_dword v8, v[0:1], off
	v_lshl_add_u64 v[0:1], v[46:47], 0, s[28:29]
	global_load_dword v9, v[0:1], off
	v_lshl_add_u64 v[0:1], v[48:49], 0, s[28:29]
	global_load_dword v10, v[0:1], off
	v_lshl_add_u64 v[0:1], v[54:55], 0, s[28:29]
	global_load_dword v11, v[0:1], off
	v_lshl_add_u64 v[0:1], v[56:57], 0, s[28:29]
	global_load_dword v12, v[0:1], off
	v_lshl_add_u64 v[0:1], v[58:59], 0, s[28:29]
	global_load_dword v13, v[0:1], off
	v_lshl_add_u64 v[0:1], v[60:61], 0, s[28:29]
	global_load_dword v14, v[0:1], off
	v_lshl_add_u64 v[0:1], v[62:63], 0, s[28:29]
	global_load_dword v15, v[0:1], off
	s_waitcnt vmcnt(0)
	ds_write2st64_b32 v203, v8, v9 offset0:120 offset1:121
	ds_write2st64_b32 v203, v10, v11 offset0:122 offset1:123
	ds_write2st64_b32 v203, v12, v13 offset0:124 offset1:125
	ds_write2st64_b32 v203, v14, v15 offset0:126 offset1:127
.LBB0_481:
	s_or_b64 exec, exec, s[0:1]
	global_load_dword v16, v[50:51], off
	v_readlane_b32 s36, v247, 13
	v_readlane_b32 s37, v247, 14
	v_readlane_b32 s38, v247, 15
	v_readlane_b32 s39, v247, 16
	v_readlane_b32 s40, v247, 17
	v_readlane_b32 s41, v247, 18
	v_readlane_b32 s42, v247, 19
	v_readlane_b32 s43, v247, 20
	v_readlane_b32 s44, v247, 21
	v_readlane_b32 s45, v247, 22
	v_readlane_b32 s46, v247, 23
	v_readlane_b32 s47, v247, 24
	v_readlane_b32 s48, v247, 25
	v_readlane_b32 s49, v247, 26
	v_readlane_b32 s50, v247, 27
	v_readlane_b32 s51, v247, 28
	s_ashr_i32 s0, s59, 4
	s_ashr_i32 s1, s0, 31
	v_mov_b32_e32 v100, v41
	v_mov_b32_e32 v101, v41
	s_waitcnt vmcnt(2)
	v_mov_b64_e32 v[98:99], v[100:101]
	v_mov_b64_e32 v[96:97], v[100:101]
	v_mov_b64_e32 v[94:95], v[100:101]
	v_add_u32_e32 v0, s58, v155
	v_lshlrev_b32_e32 v40, 7, v0
	v_lshl_add_u64 v[4:5], v[64:65], 0, v[40:41]
	v_lshl_add_u64 v[8:9], v[66:67], 0, v[40:41]
	v_lshlrev_b32_e32 v40, 8, v0
	global_load_dwordx4 v[0:3], v[4:5], off offset:16
	s_nop 0
	global_load_dwordx4 v[4:7], v[4:5], off
	v_lshl_add_u64 v[12:13], v[68:69], 0, v[40:41]
	v_add_u32_e32 v40, s58, v85
	global_load_dwordx4 v[210:213], v[8:9], off offset:16
	global_load_dwordx4 v[214:217], v[8:9], off
	global_load_dwordx4 v[218:221], v[12:13], off offset:48
	global_load_dwordx4 v[222:225], v[12:13], off offset:32
	global_load_dwordx4 v[226:229], v[12:13], off offset:16
	s_nop 0
	global_load_dwordx4 v[230:233], v[12:13], off
	s_waitcnt vmcnt(0)
	ds_write_b32 v140, v16 offset:32832
	ds_write_b128 v169, v[4:7] offset:42816
	ds_write_b128 v169, v[0:3] offset:42832
	ds_write_b128 v169, v[214:217] offset:52032
	ds_write_b128 v169, v[210:213] offset:52048
	ds_write_b128 v170, v[230:233] offset:61248
	ds_write_b128 v170, v[226:229] offset:61264
	ds_write_b128 v170, v[222:225] offset:61280
	ds_write_b128 v170, v[218:221] offset:61296
	v_lshlrev_b64 v[0:1], 2, v[40:41]
	v_lshl_add_u64 v[2:3], s[50:51], 0, v[0:1]
	v_readlane_b32 s36, v247, 29
	v_readlane_b32 s37, v247, 30
	v_readlane_b32 s38, v247, 31
	v_readlane_b32 s39, v247, 32
	v_readlane_b32 s40, v247, 33
	v_readlane_b32 s41, v247, 34
	v_readlane_b32 s42, v247, 35
	v_readlane_b32 s43, v247, 36
	v_lshl_add_u64 v[0:1], s[38:39], 0, v[0:1]
	v_readlane_b32 s36, v248, 32
	global_load_dword v207, v[2:3], off
	v_or_b32_e32 v2, s58, v156
	s_lshl_b64 s[58:59], s[0:1], 11
	v_readlane_b32 s38, v248, 34
	v_readlane_b32 s39, v248, 35
	global_load_dword v208, v[0:1], off
	v_or_b32_e32 v70, s58, v136
	v_mov_b64_e32 v[0:1], s[38:39]
	v_mad_u64_u32 v[0:1], s[0:1], v70, s90, v[0:1]
	v_mad_i32_i24 v1, s59, v204, v1
	v_lshlrev_b32_e32 v40, 1, v2
	v_lshl_add_u64 v[8:9], v[0:1], 0, v[40:41]
	v_add_co_u32_e32 v0, vcc, 0x1000, v8
	v_mov_b32_e32 v71, s59
	s_nop 0
	v_addc_co_u32_e32 v1, vcc, 0, v9, vcc
	s_waitcnt lgkmcnt(0)
	s_barrier
	global_load_dwordx2 v[88:89], v[8:9], off
	global_load_dwordx2 v[76:77], v[8:9], off offset:2048
	global_load_dwordx2 v[86:87], v[0:1], off
	v_lshlrev_b64 v[0:1], 9, v[70:71]
	v_lshl_add_u64 v[4:5], v[42:43], 0, v[0:1]
	global_load_dwordx4 v[0:3], v[4:5], off offset:16
	s_nop 0
	global_load_dwordx4 v[4:7], v[4:5], off
	v_readlane_b32 s44, v247, 37
	v_readlane_b32 s45, v247, 38
	v_readlane_b32 s46, v247, 39
	v_readlane_b32 s47, v247, 40
	v_readlane_b32 s48, v247, 41
	v_readlane_b32 s49, v247, 42
	v_readlane_b32 s50, v247, 43
	v_readlane_b32 s51, v247, 44
	v_readlane_b32 s37, v248, 33
	v_readlane_b32 s40, v248, 36
	v_readlane_b32 s41, v248, 37
	v_readlane_b32 s42, v248, 38
	v_readlane_b32 s43, v248, 39
	s_and_saveexec_b64 s[0:1], s[22:23]
	s_cbranch_execz .LBB0_483
	v_add_co_u32_e32 v10, vcc, 0xfffff000, v8
	s_nop 1
	v_addc_co_u32_e32 v11, vcc, -1, v9, vcc
	global_load_dwordx2 v[94:95], v[10:11], off offset:-2048
	global_load_dwordx2 v[96:97], v[8:9], off offset:-4096
	global_load_dwordx2 v[98:99], v[8:9], off offset:-2048
